# scan weight blocks: 8 SC-table reads issued together, counted lgkmcnt per block
# baseline (speedup 1.0000x reference)
.LBB0_647:
	s_or_b64 exec, exec, s[50:51]
	v_lshl_add_u32 v211, v170, 2, s61
	ds_read_b32 v152, v211 offset:512
	v_lshl_add_u32 v1, v140, 2, s61
	ds_read_b128 v[128:131], v1
	ds_read_b128 v[214:217], v1 offset:64
	ds_read_b128 v[218:221], v1 offset:128
	ds_read_b128 v[226:229], v1 offset:192
	ds_read_b128 v[236:239], v1 offset:256
	ds_read_b128 v[240:243], v1 offset:320
	ds_read_b128 v[244:247], v1 offset:384
	ds_read_b128 v[248:251], v1 offset:448
	v_mov_b32_e32 v2, 0
	s_and_saveexec_b64 s[50:51], s[16:17]
	s_cbranch_execz .LBB0_661
	v_readlane_b32 s62, v254, 44
	v_readlane_b32 s63, v254, 45
	s_waitcnt lgkmcnt(7)
	v_sub_f32_e32 v2, v128, v152
	v_mul_f32_e32 v2, 0x3fb8aa3b, v2
	v_exp_f32_e32 v2, v2
	v_sub_f32_e32 v3, v129, v152
	v_mul_f32_e32 v3, 0x3fb8aa3b, v3
	v_sub_f32_e32 v128, v130, v152
	v_cndmask_b32_e64 v2, v2, 0, s[62:63]
	v_exp_f32_e32 v3, v3
	v_mul_f32_e32 v129, 0x3fb8aa3b, v128
	v_mul_f32_e32 v128, v100, v2
	v_fma_f32 v100, v100, v2, 0
	v_sub_f32_e32 v2, v131, v152
	v_mul_f32_e32 v2, 0x3fb8aa3b, v2
	v_readlane_b32 s62, v254, 46
	v_exp_f32_e32 v2, v2
	v_readlane_b32 s63, v254, 47
	v_exp_f32_e32 v130, v129
	s_nop 0
	v_cndmask_b32_e64 v3, 0, v3, s[62:63]
	v_readlane_b32 s62, v254, 48
	v_readlane_b32 s63, v254, 49
	v_mul_f32_e32 v129, v101, v3
	v_fmac_f32_e32 v100, v101, v3
	v_cndmask_b32_e64 v3, v2, 0, s[62:63]
	v_readlane_b32 s62, v254, 50
	v_readlane_b32 s63, v254, 51
	s_nop 1
	v_cndmask_b32_e64 v2, v130, 0, s[62:63]
	v_pk_mul_f32 v[130:131], v[102:103], v[2:3]
	s_nop 0
	v_add_f32_e32 v2, v130, v100
	v_mov_b64_e32 v[100:101], v[128:129]
	v_add_f32_e32 v2, v131, v2
	v_mov_b64_e32 v[102:103], v[130:131]
	s_or_b64 exec, exec, s[50:51]
	s_and_saveexec_b64 s[50:51], s[18:19]
	s_cbranch_execnz .LBB0_662

.LBB0_650:
	v_readlane_b32 s62, v254, 60
	v_readlane_b32 s63, v254, 61
	s_waitcnt lgkmcnt(5)
	v_sub_f32_e32 v3, v218, v152
	v_sub_f32_e32 v128, v219, v152
	v_mul_f32_e32 v128, 0x3fb8aa3b, v128
	v_exp_f32_e32 v128, v128
	v_mul_f32_e32 v3, 0x3fb8aa3b, v3
	v_exp_f32_e32 v3, v3
	v_sub_f32_e32 v129, v220, v152
	v_sub_f32_e32 v130, v221, v152
	v_mul_f32_e32 v131, 0x3fb8aa3b, v129
	v_cndmask_b32_e64 v129, v128, 0, s[62:63]
	v_readlane_b32 s62, v254, 62
	v_readlane_b32 s63, v254, 63
	s_nop 1
	v_cndmask_b32_e64 v128, v3, 0, s[62:63]
	v_mul_f32_e32 v3, 0x3fb8aa3b, v130
	v_pk_mul_f32 v[108:109], v[108:109], v[128:129]
	v_exp_f32_e32 v3, v3
	v_exp_f32_e32 v128, v131
	v_readlane_b32 s62, v255, 0
	v_add_f32_e32 v2, v2, v108
	v_readlane_b32 s63, v255, 1
	v_add_f32_e32 v129, v109, v2
	v_cndmask_b32_e64 v2, v128, 0, s[66:67]
	v_cndmask_b32_e64 v3, v3, 0, s[62:63]
	v_pk_mul_f32 v[110:111], v[110:111], v[2:3]
	s_nop 0
	v_add_f32_e32 v2, v110, v129
	v_add_f32_e32 v2, v111, v2
	s_or_b64 exec, exec, s[50:51]
	s_and_saveexec_b64 s[50:51], s[22:23]
	s_cbranch_execnz .LBB0_664

.LBB0_652:
	s_waitcnt lgkmcnt(3)
	v_sub_f32_e32 v3, v236, v152
	v_sub_f32_e32 v128, v237, v152
	v_mul_f32_e32 v3, 0x3fb8aa3b, v3
	v_mul_f32_e32 v128, 0x3fb8aa3b, v128
	v_exp_f32_e32 v128, v128
	v_exp_f32_e32 v3, v3
	v_sub_f32_e32 v129, v238, v152
	v_sub_f32_e32 v130, v239, v152
	v_mul_f32_e32 v131, 0x3fb8aa3b, v129
	v_cndmask_b32_e64 v129, v128, 0, s[76:77]
	v_cndmask_b32_e64 v128, v3, 0, s[78:79]
	v_mul_f32_e32 v3, 0x3fb8aa3b, v130
	v_pk_mul_f32 v[116:117], v[116:117], v[128:129]
	v_exp_f32_e32 v3, v3
	v_exp_f32_e32 v128, v131
	v_add_f32_e32 v2, v2, v116
	v_add_f32_e32 v129, v117, v2
	v_cndmask_b32_e64 v3, v3, 0, s[80:81]
	v_cndmask_b32_e64 v2, v128, 0, s[82:83]
	v_pk_mul_f32 v[118:119], v[118:119], v[2:3]
	s_nop 0
	v_add_f32_e32 v2, v118, v129
	v_add_f32_e32 v2, v119, v2
	s_or_b64 exec, exec, s[50:51]
	s_and_saveexec_b64 s[50:51], s[26:27]
	s_cbranch_execnz .LBB0_666

.LBB0_654:
	s_waitcnt lgkmcnt(1)
	v_sub_f32_e32 v3, v244, v152
	v_sub_f32_e32 v128, v245, v152
	v_mul_f32_e32 v3, 0x3fb8aa3b, v3
	v_mul_f32_e32 v128, 0x3fb8aa3b, v128
	v_exp_f32_e32 v128, v128
	v_exp_f32_e32 v3, v3
	v_sub_f32_e32 v129, v246, v152
	v_sub_f32_e32 v130, v247, v152
	v_mul_f32_e32 v131, 0x3fb8aa3b, v129
	v_cndmask_b32_e64 v129, v128, 0, s[92:93]
	v_cndmask_b32_e64 v128, v3, 0, s[94:95]
	v_mul_f32_e32 v3, 0x3fb8aa3b, v130
	v_pk_mul_f32 v[124:125], v[124:125], v[128:129]
	v_exp_f32_e32 v3, v3
	v_exp_f32_e32 v128, v131
	v_add_f32_e32 v2, v2, v124
	v_add_f32_e32 v129, v125, v2
	v_cndmask_b32_e64 v3, v3, 0, s[96:97]
	v_cndmask_b32_e64 v2, v128, 0, s[4:5]
	v_pk_mul_f32 v[126:127], v[126:127], v[2:3]
	s_nop 0
	v_add_f32_e32 v2, v126, v129
	v_add_f32_e32 v2, v127, v2
	s_or_b64 exec, exec, s[50:51]
	s_and_saveexec_b64 s[50:51], s[30:31]
	s_cbranch_execnz .LBB0_668
	s_branch .LBB0_669

.LBB0_662:
	v_readlane_b32 s62, v254, 52
	v_readlane_b32 s63, v254, 53
	s_waitcnt lgkmcnt(6)
	v_sub_f32_e32 v3, v214, v152
	v_sub_f32_e32 v128, v215, v152
	v_mul_f32_e32 v128, 0x3fb8aa3b, v128
	v_exp_f32_e32 v128, v128
	v_mul_f32_e32 v3, 0x3fb8aa3b, v3
	v_exp_f32_e32 v3, v3
	v_sub_f32_e32 v129, v216, v152
	v_sub_f32_e32 v130, v217, v152
	v_mul_f32_e32 v131, 0x3fb8aa3b, v129
	v_cndmask_b32_e64 v129, v128, 0, s[62:63]
	v_readlane_b32 s62, v254, 54
	v_readlane_b32 s63, v254, 55
	s_nop 1
	v_cndmask_b32_e64 v128, v3, 0, s[62:63]
	v_mul_f32_e32 v3, 0x3fb8aa3b, v130
	v_exp_f32_e32 v3, v3
	v_pk_mul_f32 v[96:97], v[96:97], v[128:129]
	v_exp_f32_e32 v128, v131
	v_readlane_b32 s62, v254, 56
	v_readlane_b32 s63, v254, 57
	v_add_f32_e32 v2, v2, v96
	v_add_f32_e32 v129, v97, v2
	v_cndmask_b32_e64 v3, v3, 0, s[62:63]
	v_readlane_b32 s62, v254, 58
	v_readlane_b32 s63, v254, 59
	s_nop 1
	v_cndmask_b32_e64 v2, v128, 0, s[62:63]
	v_pk_mul_f32 v[98:99], v[98:99], v[2:3]
	s_nop 0
	v_add_f32_e32 v2, v98, v129
	v_add_f32_e32 v2, v99, v2
	s_or_b64 exec, exec, s[50:51]
	s_and_saveexec_b64 s[50:51], s[20:21]
	s_cbranch_execnz .LBB0_650

.LBB0_664:
	s_waitcnt lgkmcnt(4)
	v_sub_f32_e32 v3, v226, v152
	v_sub_f32_e32 v128, v227, v152
	v_mul_f32_e32 v3, 0x3fb8aa3b, v3
	v_mul_f32_e32 v128, 0x3fb8aa3b, v128
	v_exp_f32_e32 v128, v128
	v_exp_f32_e32 v3, v3
	v_sub_f32_e32 v129, v228, v152
	v_sub_f32_e32 v130, v229, v152
	v_mul_f32_e32 v131, 0x3fb8aa3b, v129
	v_cndmask_b32_e64 v129, v128, 0, s[68:69]
	v_cndmask_b32_e64 v128, v3, 0, s[70:71]
	v_mul_f32_e32 v3, 0x3fb8aa3b, v130
	v_pk_mul_f32 v[104:105], v[104:105], v[128:129]
	v_exp_f32_e32 v3, v3
	v_exp_f32_e32 v128, v131
	v_add_f32_e32 v2, v2, v104
	v_add_f32_e32 v129, v105, v2
	v_cndmask_b32_e64 v3, v3, 0, s[72:73]
	v_cndmask_b32_e64 v2, v128, 0, s[74:75]
	v_pk_mul_f32 v[106:107], v[106:107], v[2:3]
	s_nop 0
	v_add_f32_e32 v2, v106, v129
	v_add_f32_e32 v2, v107, v2
	s_or_b64 exec, exec, s[50:51]
	s_and_saveexec_b64 s[50:51], s[24:25]
	s_cbranch_execnz .LBB0_652

.LBB0_666:
	s_waitcnt lgkmcnt(2)
	v_sub_f32_e32 v3, v240, v152
	v_sub_f32_e32 v128, v241, v152
	v_mul_f32_e32 v3, 0x3fb8aa3b, v3
	v_mul_f32_e32 v128, 0x3fb8aa3b, v128
	v_exp_f32_e32 v128, v128
	v_exp_f32_e32 v3, v3
	v_sub_f32_e32 v129, v242, v152
	v_sub_f32_e32 v130, v243, v152
	v_mul_f32_e32 v131, 0x3fb8aa3b, v129
	v_cndmask_b32_e64 v129, v128, 0, s[84:85]
	v_cndmask_b32_e64 v128, v3, 0, s[86:87]
	v_mul_f32_e32 v3, 0x3fb8aa3b, v130
	v_pk_mul_f32 v[112:113], v[112:113], v[128:129]
	v_exp_f32_e32 v3, v3
	v_exp_f32_e32 v128, v131
	v_add_f32_e32 v2, v2, v112
	v_add_f32_e32 v129, v113, v2
	v_cndmask_b32_e64 v3, v3, 0, s[88:89]
	v_cndmask_b32_e64 v2, v128, 0, s[90:91]
	v_pk_mul_f32 v[114:115], v[114:115], v[2:3]
	s_nop 0
	v_add_f32_e32 v2, v114, v129
	v_add_f32_e32 v2, v115, v2
	s_or_b64 exec, exec, s[50:51]
	s_and_saveexec_b64 s[50:51], s[28:29]
	s_cbranch_execnz .LBB0_654

.LBB0_668:
	s_waitcnt lgkmcnt(0)
	v_sub_f32_e32 v1, v248, v152
	v_sub_f32_e32 v3, v249, v152
	v_mul_f32_e32 v1, 0x3fb8aa3b, v1
	v_mul_f32_e32 v3, 0x3fb8aa3b, v3
	v_exp_f32_e32 v3, v3
	v_exp_f32_e32 v1, v1
	v_sub_f32_e32 v128, v250, v152
	v_sub_f32_e32 v130, v251, v152
	v_mul_f32_e32 v131, 0x3fb8aa3b, v128
	v_cndmask_b32_e64 v129, v3, 0, s[48:49]
	v_cndmask_b32_e64 v128, v1, 0, s[0:1]
	v_mul_f32_e32 v1, 0x3fb8aa3b, v130
	v_pk_mul_f32 v[120:121], v[120:121], v[128:129]
	v_exp_f32_e32 v1, v1
	v_exp_f32_e32 v128, v131
	v_add_f32_e32 v2, v2, v120
	v_add_f32_e32 v129, v121, v2
	v_cndmask_b32_e64 v3, v1, 0, s[6:7]
	v_cndmask_b32_e64 v2, v128, 0, s[44:45]
	v_pk_mul_f32 v[122:123], v[122:123], v[2:3]
	s_nop 0
	v_add_f32_e32 v1, v122, v129
	v_add_f32_e32 v2, v123, v1
